# speedup vs baseline: 1.0068x; 1.0055x over previous
; __device__ __forceinline__ void ssd_dt_acum(const float* DT, int rb, int L, int h, float a, int lane, float& dt, float& acum) {
;   dt = (lane < L) ? DT[(long)(rb + lane) * 32 + h] : 0.f;
;   float v = dt * a;
; #pragma unroll
;   for (int o = 1; o < 64; o <<= 1) { const float t = bperm(v, lane - o); if (lane >= o) v += t; }
;   acum = v;
; }
; __device__ __forceinline__ void ssd_states_item(KP P, int l, int seq, int c, int g, char* smem) {
;     ...
;   const float a = -__expf(P->a_log[l * 32 + h]);
;   float dt, acum;
;   ssd_dt_acum(DT, rb, L, h, a, lane, dt, acum);
;   const float tot = bperm(acum, 63);
;   const float scale = dt * __expf(tot - acum);
;   if (!isS && lane == 0) CD[(seq * 64 + c) * 32 + h] = __expf(tot);
; #pragma unroll
;   for (int i = 0; i < 8; ++i) {
;     const int tok = i * 8 + (lane >> 3), vec = lane & 7;
;     const float sc = bperm(scale, tok);
;     uint4 v = make_uint4(zz, zz, zz, zz);
;     if (tok < L) {
;       float f[8];
;       unpack8(*(const uint4*)(XBC + (long)(rb + tok) * 3072 + h * 64 + vec * 8), f);
; #pragma unroll
;       for (int q = 0; q < 8; ++q) f[q] *= sc;
;       v = pack8(f);
;     }
;     *(uint4*)(Xs + tok * 72 + vec * 8) = v;
.LBB0_564:
	s_or_b64 exec, exec, s[0:1]
	v_lshlrev_b32_e32 v12, 6, v0
	v_lshlrev_b32_e32 v2, 4, v16
	v_ashrrev_i32_e32 v13, 31, v12
	v_lshrrev_b32_e32 v15, 3, v14
	v_and_b32_e32 v2, 0x70, v2
	v_lshl_add_u64 v[12:13], v[12:13], 1, s[6:7]
	v_lshl_add_u64 v[12:13], v[12:13], 0, v[2:3]
	v_or_b32_e32 v17, s15, v15
	s_movk_i32 s10, 0x1800
	v_mad_u64_u32 v[18:19], s[0:1], v17, s10, v[12:13]
	s_waitcnt vmcnt(0)
	v_mul_f32_e32 v11, 0x3fb8aa3b, v11
	global_load_dwordx4 v[18:21], v[18:19], off
	v_exp_f32_e32 v11, v11
	v_lshlrev_b32_e32 v17, 2, v14
	v_add_u32_e32 v22, -4, v17
	v_or_b32_e32 v26, 8, v15
	v_mul_f32_e64 v23, v10, -v11
	ds_bpermute_b32 v22, v22, v23
	v_cmp_eq_u32_e32 vcc, 0, v14
	v_or_b32_e32 v25, s15, v26
	v_add_u32_e32 v24, -8, v17
	v_mad_u64_u32 v[12:13], s[0:1], v25, s10, v[12:13]
	s_waitcnt lgkmcnt(0)
	v_fma_f32 v11, v10, -v11, v22
	v_cndmask_b32_e32 v11, v11, v23, vcc
	ds_bpermute_b32 v27, v24, v11
	global_load_dwordx4 v[22:25], v[12:13], off
	v_cmp_gt_u32_e64 s[6:7], 2, v14
	v_add_u32_e32 v12, -16, v17
	v_cmp_gt_u32_e32 vcc, 4, v14
	s_waitcnt lgkmcnt(0)
	v_add_f32_e32 v13, v11, v27
	v_cndmask_b32_e64 v11, v13, v11, s[6:7]
	ds_bpermute_b32 v12, v12, v11
	v_subrev_u32_e32 v13, 32, v17
	s_movk_i32 s0, 0x2400
	v_mul_lo_u32 v9, v9, s0
	s_add_i32 s26, s18, s60
	s_waitcnt lgkmcnt(0)
	v_add_f32_e32 v12, v11, v12
	v_cndmask_b32_e32 v11, v12, v11, vcc
	ds_bpermute_b32 v12, v13, v11
	v_cmp_gt_u32_e32 vcc, 8, v14
	v_subrev_u32_e32 v13, 64, v17
	s_lshl_b64 s[6:7], s[26:27], 18
	v_lshlrev_b64 v[0:1], 13, v[0:1]
	s_waitcnt lgkmcnt(0)
	v_add_f32_e32 v12, v11, v12
	v_cndmask_b32_e32 v11, v12, v11, vcc
	ds_bpermute_b32 v12, v13, v11
	v_add_u32_e32 v13, 0xffffff80, v17
	v_cmp_gt_u32_e32 vcc, 32, v14
	v_add_u32_e32 v17, 0, v9
	v_lshl_add_u64 v[0:1], v[0:1], 0, s[6:7]
	s_waitcnt lgkmcnt(0)
	v_add_f32_e32 v12, v11, v12
	v_cndmask_b32_e64 v11, v12, v11, s[4:5]
	ds_bpermute_b32 v12, v13, v11
	v_or_b32_e32 v91, 16, v85
	v_or_b32_e32 v92, 32, v85
	v_or_b32_e32 v94, 48, v85
	v_or_b32_e32 v93, 64, v85
	s_waitcnt lgkmcnt(0)
	v_add_f32_e32 v9, v11, v12
	v_cndmask_b32_e32 v9, v9, v11, vcc
	v_lshlrev_b32_e32 v11, 2, v15
	v_readlane_b32 s0, v9, 63
	v_mul_u32_u24_e32 v12, 0x90, v15
	v_add3_u32 v15, v17, v2, v12
	v_sub_f32_e32 v9, s0, v9
	v_mul_f32_e32 v9, 0x3fb8aa3b, v9
	v_exp_f32_e32 v9, v9
	v_or_b32_e32 v90, 0x50, v85
	v_or_b32_e32 v89, 0x60, v85
	v_readlane_b32 s6, v252, 3
	v_mul_f32_e32 v9, v10, v9
	ds_bpermute_b32 v2, v11, v9
	v_readlane_b32 s7, v252, 4
	s_movk_i32 s19, 0x1800
	s_waitcnt vmcnt(1)
	v_and_b32_e32 v11, 0xffff0000, v19
	v_and_b32_e32 v10, 0xffff0000, v18
	v_lshlrev_b32_e32 v13, 16, v19
	v_lshlrev_b32_e32 v12, 16, v18
	v_and_b32_e32 v19, 0xffff0000, v21
	v_and_b32_e32 v18, 0xffff0000, v20
	v_lshlrev_b32_e32 v21, 16, v21
	v_lshlrev_b32_e32 v20, 16, v20
	s_waitcnt lgkmcnt(0)
	v_pk_mul_f32 v[10:11], v[2:3], v[10:11] op_sel_hi:[0,1]
	v_pk_mul_f32 v[12:13], v[2:3], v[12:13] op_sel_hi:[0,1]
	v_pk_mul_f32 v[18:19], v[2:3], v[18:19] op_sel_hi:[0,1]
	v_pk_mul_f32 v[20:21], v[2:3], v[20:21] op_sel_hi:[0,1]
	v_and_b32_sdwa v2, v11, v226 dst_sel:DWORD dst_unused:UNUSED_PAD src0_sel:WORD_1 src1_sel:DWORD
	v_and_b32_sdwa v27, v10, v226 dst_sel:DWORD dst_unused:UNUSED_PAD src0_sel:WORD_1 src1_sel:DWORD
	v_and_b32_sdwa v28, v13, v226 dst_sel:DWORD dst_unused:UNUSED_PAD src0_sel:WORD_1 src1_sel:DWORD
	v_add3_u32 v2, v11, v2, s33
	v_and_b32_sdwa v29, v12, v226 dst_sel:DWORD dst_unused:UNUSED_PAD src0_sel:WORD_1 src1_sel:DWORD
	v_and_b32_sdwa v30, v19, v226 dst_sel:DWORD dst_unused:UNUSED_PAD src0_sel:WORD_1 src1_sel:DWORD
	v_add3_u32 v10, v10, v27, s33
	v_add3_u32 v11, v13, v28, s33
	v_and_b32_e32 v2, 0xffff0000, v2
	v_and_b32_sdwa v32, v21, v226 dst_sel:DWORD dst_unused:UNUSED_PAD src0_sel:WORD_1 src1_sel:DWORD
	v_add3_u32 v12, v12, v29, s33
	v_add3_u32 v13, v19, v30, s33
	v_and_b32_e32 v10, 0xffff0000, v10
	v_or_b32_sdwa v11, v2, v11 dst_sel:DWORD dst_unused:UNUSED_PAD src0_sel:DWORD src1_sel:WORD_1
	v_and_b32_sdwa v2, v20, v226 dst_sel:DWORD dst_unused:UNUSED_PAD src0_sel:WORD_1 src1_sel:DWORD
	v_and_b32_e32 v13, 0xffff0000, v13
	v_or_b32_sdwa v10, v10, v12 dst_sel:DWORD dst_unused:UNUSED_PAD src0_sel:DWORD src1_sel:WORD_1
	v_add3_u32 v12, v20, v2, s33
	v_add3_u32 v2, v21, v32, s33
	v_or_b32_sdwa v13, v13, v2 dst_sel:DWORD dst_unused:UNUSED_PAD src0_sel:DWORD src1_sel:WORD_1
	v_lshlrev_b32_e32 v2, 2, v26
	v_and_b32_sdwa v31, v18, v226 dst_sel:DWORD dst_unused:UNUSED_PAD src0_sel:WORD_1 src1_sel:DWORD
	ds_bpermute_b32 v2, v2, v9
	v_add3_u32 v18, v18, v31, s33
	v_and_b32_e32 v18, 0xffff0000, v18
	v_or_b32_sdwa v12, v18, v12 dst_sel:DWORD dst_unused:UNUSED_PAD src0_sel:DWORD src1_sel:WORD_1
	ds_write_b128 v15, v[10:13] offset:17408
	s_waitcnt vmcnt(0)
	v_and_b32_e32 v11, 0xffff0000, v23
	v_and_b32_e32 v10, 0xffff0000, v22
	s_waitcnt lgkmcnt(1)
; __device__ __forceinline__ bf16x8 cat44(s16x4 a, s16x4 b) { return (bf16x8){a[0], a[1], a[2], a[3], b[0], b[1], b[2], b[3]}; }
; __device__ __forceinline__ void ssd_states_item(KP P, int l, int seq, int c, int g, char* smem) {
;     ...
;   __syncthreads();
;   f32x4 acc[4][8] = {};
;   const int trr = (lane >> 4) * 8 + ((lane >> 2) & 3), trc = (lane & 3) * 4;
; #pragma unroll
;   for (int ks = 0; ks < 2; ++ks) {
;     bf16x8 af[4];
; #pragma unroll
;     for (int mb = 0; mb < 4; ++mb) {
;       const u16* p0 = Xs + (ks * 32 + trr) * 72 + mb * 16 + trc;
;       af[mb] = cat44(ldtr(p0), ldtr(p0 + 4 * 72));
;     }
; #pragma unroll
;     for (int nb = 0; nb < 8; ++nb) {
;       const u16* p0 = Bs + (ks * 32 + trr) * 136 + nb * 16 + trc;
;       const bf16x8 bf = cat44(ldtr(p0), ldtr(p0 + 4 * 136));
; #pragma unroll
;       for (int mb = 0; mb < 4; ++mb) acc[mb][nb] = __builtin_amdgcn_mfma_f32_16x16x32_bf16(af[mb], bf, acc[mb][nb], 0, 0, 0);
;     }
;   }
;   if (!isS) {
;     u16* dst = (u16*)ST + ((long)(seq * 64 + c) * 32 + h) * 8192;
; #pragma unroll
;     for (int mb = 0; mb < 4; ++mb)
; #pragma unroll
;       for (int nb = 0; nb < 8; ++nb)
; #pragma unroll
;         for (int j = 0; j < 4; ++j) dst[(mb * 16 + (lane >> 4) * 4 + j) * 128 + nb * 16 + (lane & 15)] = f2bf(acc[mb][nb][j]);
;   } else {
;     const int bs = seq - 2;
;     const float* h0 = P->st_ssm + ((long)(l * 8 + bs) * 32 + h) * 8192;
;     float* dst = P->out + O_SSMS + ((long)(l * 8 + bs) * 32 + h) * 8192;
;     const float bd = __expf(tot);
; #pragma unroll
;     for (int mb = 0; mb < 4; ++mb)
; #pragma unroll
;       for (int nb = 0; nb < 8; ++nb)
; #pragma unroll
;         for (int j = 0; j < 4; ++j) {
;           const int o = (mb * 16 + (lane >> 4) * 4 + j) * 128 + nb * 16 + (lane & 15);
;           dst[o] = h0[o] * bd + acc[mb][nb][j];
;         }
	v_pk_mul_f32 v[10:11], v[2:3], v[10:11] op_sel_hi:[0,1]
	v_lshlrev_b32_e32 v13, 16, v23
	v_lshlrev_b32_e32 v12, 16, v22
	v_pk_mul_f32 v[12:13], v[2:3], v[12:13] op_sel_hi:[0,1]
	v_and_b32_sdwa v18, v10, v226 dst_sel:DWORD dst_unused:UNUSED_PAD src0_sel:WORD_1 src1_sel:DWORD
	v_and_b32_sdwa v9, v11, v226 dst_sel:DWORD dst_unused:UNUSED_PAD src0_sel:WORD_1 src1_sel:DWORD
	v_add3_u32 v10, v10, v18, s33
	v_and_b32_sdwa v18, v12, v226 dst_sel:DWORD dst_unused:UNUSED_PAD src0_sel:WORD_1 src1_sel:DWORD
	v_add3_u32 v9, v11, v9, s33
	v_and_b32_e32 v10, 0xffff0000, v10
	v_and_b32_sdwa v11, v13, v226 dst_sel:DWORD dst_unused:UNUSED_PAD src0_sel:WORD_1 src1_sel:DWORD
	v_add3_u32 v12, v12, v18, s33
	v_add3_u32 v11, v13, v11, s33
	v_or_b32_sdwa v10, v10, v12 dst_sel:DWORD dst_unused:UNUSED_PAD src0_sel:DWORD src1_sel:WORD_1
	v_and_b32_e32 v13, 0xffff0000, v25
	v_and_b32_e32 v12, 0xffff0000, v24
	v_and_b32_e32 v9, 0xffff0000, v9
	v_pk_mul_f32 v[12:13], v[2:3], v[12:13] op_sel_hi:[0,1]
	v_lshlrev_b32_e32 v19, 16, v25
	v_lshlrev_b32_e32 v18, 16, v24
	v_or_b32_sdwa v11, v9, v11 dst_sel:DWORD dst_unused:UNUSED_PAD src0_sel:DWORD src1_sel:WORD_1
	v_pk_mul_f32 v[18:19], v[2:3], v[18:19] op_sel_hi:[0,1]
	v_and_b32_sdwa v2, v13, v226 dst_sel:DWORD dst_unused:UNUSED_PAD src0_sel:WORD_1 src1_sel:DWORD
	v_and_b32_sdwa v9, v12, v226 dst_sel:DWORD dst_unused:UNUSED_PAD src0_sel:WORD_1 src1_sel:DWORD
	v_add3_u32 v2, v13, v2, s33
	v_add3_u32 v9, v12, v9, s33
	v_and_b32_sdwa v12, v19, v226 dst_sel:DWORD dst_unused:UNUSED_PAD src0_sel:WORD_1 src1_sel:DWORD
	v_and_b32_sdwa v13, v18, v226 dst_sel:DWORD dst_unused:UNUSED_PAD src0_sel:WORD_1 src1_sel:DWORD
	v_and_b32_e32 v2, 0xffff0000, v2
	v_and_b32_e32 v9, 0xffff0000, v9
	v_add3_u32 v18, v18, v13, s33
	v_add3_u32 v12, v19, v12, s33
	v_or_b32_sdwa v13, v2, v12 dst_sel:DWORD dst_unused:UNUSED_PAD src0_sel:DWORD src1_sel:WORD_1
	v_or_b32_sdwa v12, v9, v18 dst_sel:DWORD dst_unused:UNUSED_PAD src0_sel:DWORD src1_sel:WORD_1
	ds_write_b128 v15, v[10:13] offset:18560
	v_mov_b32_e32 v9, v8
	v_mov_b32_e32 v10, v8
	v_mov_b32_e32 v11, v8
	ds_write_b128 v15, v[8:11] offset:19712
	ds_write_b128 v15, v[8:11] offset:20864
	ds_write_b128 v15, v[8:11] offset:22016
	ds_write_b128 v15, v[8:11] offset:23168
	ds_write_b128 v15, v[8:11] offset:24320
	ds_write_b128 v15, v[8:11] offset:25472
	s_waitcnt lgkmcnt(0)
	s_barrier
	s_load_dwordx2 s[4:5], s[8:9], 0x20
	v_lshrrev_b32_e32 v8, 4, v14
	v_lshlrev_b32_e32 v87, 9, v8
	v_lshlrev_b64 v[18:19], 2, v[0:1]
	v_or_b32_e32 v2, v87, v85
	s_waitcnt lgkmcnt(0)
	v_lshl_add_u64 v[0:1], s[4:5], 0, v[18:19]
	v_lshlrev_b32_e32 v2, 2, v2
	v_lshl_add_u64 v[12:13], v[0:1], 0, v[2:3]
	global_load_dword v20, v[12:13], off
	v_bfe_u32 v9, v16, 2, 2
	v_lshl_or_b32 v8, v8, 3, v9
	v_lshlrev_b32_e32 v9, 3, v16
	v_and_b32_e32 v9, 24, v9
	v_mul_u32_u24_e32 v10, 0x90, v8
	v_add3_u32 v95, v17, v9, v10
	ds_read_b64_tr_b16 v[72:73], v95 offset:17408
	ds_read_b64_tr_b16 v[74:75], v95 offset:17984
	v_mul_u32_u24_e32 v8, 0x110, v8
	v_add3_u32 v88, 0, v9, v8
	ds_read_b64_tr_b16 v[70:71], v88 offset:1088
	ds_read_b64_tr_b16 v[68:69], v88
	ds_read_b64_tr_b16 v[76:77], v95 offset:22016
	ds_read_b64_tr_b16 v[78:79], v95 offset:22592
	ds_read_b64_tr_b16 v[8:9], v88 offset:8704
	ds_read_b64_tr_b16 v[10:11], v88 offset:9792
	s_waitcnt lgkmcnt(4)
	v_mfma_f32_16x16x32_bf16 v[14:17], v[72:75], v[68:71], 0
	s_load_dwordx2 s[4:5], s[8:9], 0xd0
	v_mul_f32_e32 v21, s0, v233
	v_exp_f32_e32 v86, v21
	s_waitcnt lgkmcnt(0)
	v_mfma_f32_16x16x32_bf16 v[14:17], v[76:79], v[8:11], v[14:17]
	s_mov_b64 s[0:1], 0x6900000
	v_lshl_add_u64 v[18:19], s[4:5], 0, v[18:19]
	v_lshl_add_u64 v[80:81], v[18:19], 0, s[0:1]
	v_lshl_add_u64 v[82:83], v[80:81], 0, v[2:3]
	v_or_b32_e32 v104, 0x800, v87
	v_or_b32_e32 v105, 0x880, v87
	v_or_b32_e32 v100, v105, v85
	v_or_b32_e32 v106, 0x900, v87
	v_or_b32_e32 v107, 0x980, v87
	v_or_b32_e32 v109, v105, v91
	v_or_b32_e32 v110, 0x1180, v87
	s_mov_b64 s[0:1], 0
	global_load_dword v208, v[12:13], off offset:512
	global_load_dword v209, v[12:13], off offset:1024
	global_load_dword v210, v[12:13], off offset:1536
	s_waitcnt vmcnt(0)
	v_fma_f32 v14, v86, v20, v14
	global_store_dword v[82:83], v14, off
	v_mov_b32_e32 v2, v208
	v_fma_f32 v2, v86, v2, v15
	global_store_dword v[82:83], v2, off offset:512
	v_mov_b32_e32 v2, v209
	v_fma_f32 v2, v86, v2, v16
	global_store_dword v[82:83], v2, off offset:1024
	v_mov_b32_e32 v2, v210
	v_fmac_f32_e32 v17, v86, v2
	global_store_dword v[82:83], v17, off offset:1536
	global_load_dword v20, v[12:13], off offset:64
	ds_read_b64_tr_b16 v[40:41], v88 offset:32
	ds_read_b64_tr_b16 v[42:43], v88 offset:1120
	ds_read_b64_tr_b16 v[32:33], v88 offset:8736
	ds_read_b64_tr_b16 v[34:35], v88 offset:9824
	s_waitcnt lgkmcnt(2)
	v_mfma_f32_16x16x32_bf16 v[14:17], v[72:75], v[40:43], 0
	v_or_b32_e32 v2, v87, v91
	v_lshlrev_b32_e32 v2, 2, v2
	v_lshl_add_u64 v[18:19], v[0:1], 0, v[2:3]
	s_waitcnt lgkmcnt(0)
	v_mfma_f32_16x16x32_bf16 v[14:17], v[76:79], v[32:35], v[14:17]
	global_load_dword v208, v[18:19], off offset:512
	global_load_dword v209, v[18:19], off offset:1024
	global_load_dword v210, v[18:19], off offset:1536
	s_waitcnt vmcnt(0)
	s_nop 6
	v_fma_f32 v14, v86, v20, v14
	global_store_dword v[82:83], v14, off offset:64
	v_mov_b32_e32 v14, v208
	v_lshl_add_u64 v[20:21], v[80:81], 0, v[2:3]
	v_fma_f32 v2, v86, v14, v15
	global_store_dword v[20:21], v2, off offset:512
	v_mov_b32_e32 v2, v209
	v_fma_f32 v2, v86, v2, v16
	global_store_dword v[20:21], v2, off offset:1024
	v_mov_b32_e32 v2, v210
	v_fmac_f32_e32 v17, v86, v2
	global_store_dword v[20:21], v17, off offset:1536
	global_load_dword v20, v[12:13], off offset:128
	ds_read_b64_tr_b16 v[52:53], v88 offset:64
	ds_read_b64_tr_b16 v[54:55], v88 offset:1152
	ds_read_b64_tr_b16 v[44:45], v88 offset:8768
	ds_read_b64_tr_b16 v[46:47], v88 offset:9856
	s_waitcnt lgkmcnt(2)
; __device__ __forceinline__ void ssd_states_item(KP P, int l, int seq, int c, int g, char* smem) {
;     ...
;   } else {
;     const int bs = seq - 2;
;     const float* h0 = P->st_ssm + ((long)(l * 8 + bs) * 32 + h) * 8192;
;     float* dst = P->out + O_SSMS + ((long)(l * 8 + bs) * 32 + h) * 8192;
;     const float bd = __expf(tot);
; #pragma unroll
;     for (int mb = 0; mb < 4; ++mb)
; #pragma unroll
;       for (int nb = 0; nb < 8; ++nb)
; #pragma unroll
;         for (int j = 0; j < 4; ++j) {
;           const int o = (mb * 16 + (lane >> 4) * 4 + j) * 128 + nb * 16 + (lane & 15);
;           dst[o] = h0[o] * bd + acc[mb][nb][j];
;         }
	v_mfma_f32_16x16x32_bf16 v[14:17], v[72:75], v[52:55], 0
	v_or_b32_e32 v2, v87, v92
	v_lshlrev_b32_e32 v2, 2, v2
	v_lshl_add_u64 v[18:19], v[0:1], 0, v[2:3]
	s_waitcnt lgkmcnt(0)
	v_mfma_f32_16x16x32_bf16 v[14:17], v[76:79], v[44:47], v[14:17]
	global_load_dword v208, v[18:19], off offset:512
	global_load_dword v209, v[18:19], off offset:1024
	global_load_dword v210, v[18:19], off offset:1536
	s_waitcnt vmcnt(0)
	s_nop 6
	v_fma_f32 v14, v86, v20, v14
	global_store_dword v[82:83], v14, off offset:128
	v_mov_b32_e32 v14, v208
	v_lshl_add_u64 v[20:21], v[80:81], 0, v[2:3]
	v_fma_f32 v2, v86, v14, v15
	global_store_dword v[20:21], v2, off offset:512
	v_mov_b32_e32 v2, v209
	v_fma_f32 v2, v86, v2, v16
	global_store_dword v[20:21], v2, off offset:1024
	v_mov_b32_e32 v2, v210
	v_fmac_f32_e32 v17, v86, v2
	global_store_dword v[20:21], v17, off offset:1536
	global_load_dword v20, v[12:13], off offset:192
	ds_read_b64_tr_b16 v[64:65], v88 offset:96
	ds_read_b64_tr_b16 v[66:67], v88 offset:1184
	ds_read_b64_tr_b16 v[60:61], v88 offset:8800
	ds_read_b64_tr_b16 v[62:63], v88 offset:9888
	s_waitcnt lgkmcnt(2)
	v_mfma_f32_16x16x32_bf16 v[14:17], v[72:75], v[64:67], 0
	v_or_b32_e32 v2, v87, v94
	v_lshlrev_b32_e32 v2, 2, v2
	v_lshl_add_u64 v[18:19], v[0:1], 0, v[2:3]
	s_waitcnt lgkmcnt(0)
	v_mfma_f32_16x16x32_bf16 v[14:17], v[76:79], v[60:63], v[14:17]
	global_load_dword v208, v[18:19], off offset:512
	global_load_dword v209, v[18:19], off offset:1024
	global_load_dword v210, v[18:19], off offset:1536
	s_waitcnt vmcnt(0)
	s_nop 6
	v_fma_f32 v14, v86, v20, v14
	global_store_dword v[82:83], v14, off offset:192
	v_mov_b32_e32 v14, v208
	v_lshl_add_u64 v[20:21], v[80:81], 0, v[2:3]
	v_fma_f32 v2, v86, v14, v15
	global_store_dword v[20:21], v2, off offset:512
	v_mov_b32_e32 v2, v209
	v_fma_f32 v2, v86, v2, v16
	global_store_dword v[20:21], v2, off offset:1024
	v_mov_b32_e32 v2, v210
	v_fmac_f32_e32 v17, v86, v2
	global_store_dword v[20:21], v17, off offset:1536
	global_load_dword v20, v[12:13], off offset:256
	ds_read_b64_tr_b16 v[56:57], v88 offset:128
	ds_read_b64_tr_b16 v[58:59], v88 offset:1216
	ds_read_b64_tr_b16 v[48:49], v88 offset:8832
	ds_read_b64_tr_b16 v[50:51], v88 offset:9920
	s_waitcnt lgkmcnt(2)
	v_mfma_f32_16x16x32_bf16 v[14:17], v[72:75], v[56:59], 0
	v_or_b32_e32 v2, v87, v93
	v_lshlrev_b32_e32 v2, 2, v2
	v_lshl_add_u64 v[18:19], v[0:1], 0, v[2:3]
	s_waitcnt lgkmcnt(0)
	v_mfma_f32_16x16x32_bf16 v[14:17], v[76:79], v[48:51], v[14:17]
	global_load_dword v208, v[18:19], off offset:512
	global_load_dword v209, v[18:19], off offset:1024
	global_load_dword v210, v[18:19], off offset:1536
	s_waitcnt vmcnt(0)
	s_nop 6
	v_fma_f32 v14, v86, v20, v14
	global_store_dword v[82:83], v14, off offset:256
	v_mov_b32_e32 v14, v208
	v_lshl_add_u64 v[20:21], v[80:81], 0, v[2:3]
	v_fma_f32 v2, v86, v14, v15
	global_store_dword v[20:21], v2, off offset:512
	v_mov_b32_e32 v2, v209
	v_fma_f32 v2, v86, v2, v16
	global_store_dword v[20:21], v2, off offset:1024
	v_mov_b32_e32 v2, v210
	v_fmac_f32_e32 v17, v86, v2
	global_store_dword v[20:21], v17, off offset:1536
	global_load_dword v20, v[12:13], off offset:320
	ds_read_b64_tr_b16 v[36:37], v88 offset:160
	ds_read_b64_tr_b16 v[38:39], v88 offset:1248
	ds_read_b64_tr_b16 v[28:29], v88 offset:8864
	ds_read_b64_tr_b16 v[30:31], v88 offset:9952
	s_waitcnt lgkmcnt(2)
	v_mfma_f32_16x16x32_bf16 v[14:17], v[72:75], v[36:39], 0
	v_or_b32_e32 v2, v87, v90
	v_lshlrev_b32_e32 v2, 2, v2
	v_lshl_add_u64 v[18:19], v[0:1], 0, v[2:3]
	s_waitcnt lgkmcnt(0)
	v_mfma_f32_16x16x32_bf16 v[14:17], v[76:79], v[28:31], v[14:17]
	global_load_dword v208, v[18:19], off offset:512
	global_load_dword v209, v[18:19], off offset:1024
	global_load_dword v210, v[18:19], off offset:1536
	s_waitcnt vmcnt(0)
	s_nop 6
	v_fma_f32 v14, v86, v20, v14
	global_store_dword v[82:83], v14, off offset:320
	v_mov_b32_e32 v14, v208
	v_lshl_add_u64 v[20:21], v[80:81], 0, v[2:3]
	v_fma_f32 v2, v86, v14, v15
	global_store_dword v[20:21], v2, off offset:512
	v_mov_b32_e32 v2, v209
	v_fma_f32 v2, v86, v2, v16
	global_store_dword v[20:21], v2, off offset:1024
	v_mov_b32_e32 v2, v210
	v_fmac_f32_e32 v17, v86, v2
	global_store_dword v[20:21], v17, off offset:1536
	global_load_dword v96, v[12:13], off offset:384
	ds_read_b64_tr_b16 v[24:25], v88 offset:192
	ds_read_b64_tr_b16 v[26:27], v88 offset:1280
	ds_read_b64_tr_b16 v[20:21], v88 offset:8896
	ds_read_b64_tr_b16 v[22:23], v88 offset:9984
	s_waitcnt lgkmcnt(2)
	v_mfma_f32_16x16x32_bf16 v[14:17], v[72:75], v[24:27], 0
	v_or_b32_e32 v2, v87, v89
	v_lshlrev_b32_e32 v2, 2, v2
	v_lshl_add_u64 v[18:19], v[0:1], 0, v[2:3]
	s_waitcnt lgkmcnt(0)
	v_mfma_f32_16x16x32_bf16 v[14:17], v[76:79], v[20:23], v[14:17]
	global_load_dword v208, v[18:19], off offset:512
	global_load_dword v209, v[18:19], off offset:1024
	global_load_dword v210, v[18:19], off offset:1536
	s_waitcnt vmcnt(0)
	s_nop 6
	v_fma_f32 v14, v86, v96, v14
	global_store_dword v[82:83], v14, off offset:384
	v_mov_b32_e32 v14, v208
	v_lshl_add_u64 v[96:97], v[80:81], 0, v[2:3]
	v_fma_f32 v2, v86, v14, v15
	global_store_dword v[96:97], v2, off offset:512
	v_mov_b32_e32 v2, v209
	v_fma_f32 v2, v86, v2, v16
	global_store_dword v[96:97], v2, off offset:1024
	v_mov_b32_e32 v2, v210
	v_fmac_f32_e32 v17, v86, v2
	global_store_dword v[96:97], v17, off offset:1536
	global_load_dword v96, v[12:13], off offset:448
	ds_read_b64_tr_b16 v[16:17], v88 offset:224
	ds_read_b64_tr_b16 v[18:19], v88 offset:1312
	ds_read_b64_tr_b16 v[12:13], v88 offset:8928
	ds_read_b64_tr_b16 v[14:15], v88 offset:10016
	s_waitcnt lgkmcnt(2)
; __device__ __forceinline__ void ssd_states_item(KP P, int l, int seq, int c, int g, char* smem) {
;     ...
;   } else {
;     const int bs = seq - 2;
;     const float* h0 = P->st_ssm + ((long)(l * 8 + bs) * 32 + h) * 8192;
;     float* dst = P->out + O_SSMS + ((long)(l * 8 + bs) * 32 + h) * 8192;
;     const float bd = __expf(tot);
; #pragma unroll
;     for (int mb = 0; mb < 4; ++mb)
; #pragma unroll
;       for (int nb = 0; nb < 8; ++nb)
; #pragma unroll
;         for (int j = 0; j < 4; ++j) {
;           const int o = (mb * 16 + (lane >> 4) * 4 + j) * 128 + nb * 16 + (lane & 15);
;           dst[o] = h0[o] * bd + acc[mb][nb][j];
;         }
	v_mfma_f32_16x16x32_bf16 v[72:75], v[72:75], v[16:19], 0
	v_or_b32_e32 v88, 0x70, v85
	v_or_b32_e32 v2, v87, v88
	v_lshlrev_b32_e32 v2, 2, v2
	s_waitcnt lgkmcnt(0)
	v_mfma_f32_16x16x32_bf16 v[72:75], v[76:79], v[12:15], v[72:75]
	v_lshl_add_u64 v[76:77], v[0:1], 0, v[2:3]
	v_lshl_add_u64 v[78:79], v[80:81], 0, v[2:3]
	s_waitcnt vmcnt(0)
	s_nop 4
	v_fma_f32 v72, v86, v96, v72
	global_load_dword v72, v[76:77], off offset:512
	global_store_dword v[82:83], v72, off offset:448
	s_waitcnt vmcnt(1)
	v_fma_f32 v2, v86, v72, v73
	global_load_dword v2, v[76:77], off offset:1024
	global_store_dword v[78:79], v2, off offset:512
	s_waitcnt vmcnt(1)
	v_fma_f32 v2, v86, v2, v74
	global_load_dword v74, v[76:77], off offset:1536
	global_store_dword v[78:79], v2, off offset:1024
	v_or_b32_e32 v2, v104, v85
	v_lshlrev_b32_e32 v2, 2, v2
	v_lshl_add_u64 v[72:73], v[0:1], 0, v[2:3]
	v_lshl_add_u64 v[82:83], v[80:81], 0, v[2:3]
	v_lshlrev_b32_e32 v2, 2, v100
	v_lshl_add_u64 v[100:101], v[0:1], 0, v[2:3]
	s_waitcnt vmcnt(1)
	v_fmac_f32_e32 v75, v86, v74
	global_load_dword v102, v[72:73], off
	global_store_dword v[78:79], v75, off offset:1536
	ds_read_b64_tr_b16 v[72:73], v95 offset:17440
	ds_read_b64_tr_b16 v[74:75], v95 offset:18016
	ds_read_b64_tr_b16 v[76:77], v95 offset:22048
	ds_read_b64_tr_b16 v[78:79], v95 offset:22624
	s_waitcnt lgkmcnt(2)
	v_mfma_f32_16x16x32_bf16 v[96:99], v[72:75], v[68:71], 0
	s_waitcnt lgkmcnt(0)
	v_mfma_f32_16x16x32_bf16 v[96:99], v[76:79], v[8:11], v[96:99]
	s_waitcnt vmcnt(1)
	s_nop 6
	v_fma_f32 v96, v86, v102, v96
	global_load_dword v96, v[100:101], off
	global_store_dword v[82:83], v96, off
	v_or_b32_e32 v100, v106, v85
	v_lshl_add_u64 v[82:83], v[80:81], 0, v[2:3]
	v_lshlrev_b32_e32 v2, 2, v100
	v_lshl_add_u64 v[100:101], v[0:1], 0, v[2:3]
	s_waitcnt vmcnt(1)
	v_fma_f32 v96, v86, v96, v97
	global_load_dword v100, v[100:101], off
	global_store_dword v[82:83], v96, off
	v_or_b32_e32 v96, v107, v85
	v_lshl_add_u64 v[82:83], v[80:81], 0, v[2:3]
	v_lshlrev_b32_e32 v2, 2, v96
	v_lshl_add_u64 v[96:97], v[0:1], 0, v[2:3]
	s_waitcnt vmcnt(1)
	v_fma_f32 v98, v86, v100, v98
	global_load_dword v98, v[96:97], off
	global_store_dword v[82:83], v98, off
	v_or_b32_e32 v96, v104, v91
	v_lshl_add_u64 v[82:83], v[80:81], 0, v[2:3]
	v_lshlrev_b32_e32 v2, 2, v96
	v_lshl_add_u64 v[96:97], v[0:1], 0, v[2:3]
	v_mfma_f32_16x16x32_bf16 v[100:103], v[72:75], v[40:43], 0
	s_waitcnt vmcnt(1)
	v_fmac_f32_e32 v99, v86, v98
	global_load_dword v108, v[96:97], off
	global_store_dword v[82:83], v99, off
	v_mfma_f32_16x16x32_bf16 v[96:99], v[76:79], v[32:35], v[100:103]
	v_lshl_add_u64 v[82:83], v[80:81], 0, v[2:3]
	v_lshlrev_b32_e32 v2, 2, v109
	v_or_b32_e32 v109, v105, v92
	v_lshl_add_u64 v[100:101], v[0:1], 0, v[2:3]
	s_waitcnt vmcnt(1)
	s_nop 2
	v_fma_f32 v96, v86, v108, v96
	global_load_dword v96, v[100:101], off
	global_store_dword v[82:83], v96, off
	v_or_b32_e32 v100, v106, v91
	v_lshl_add_u64 v[82:83], v[80:81], 0, v[2:3]
	v_lshlrev_b32_e32 v2, 2, v100
	v_lshl_add_u64 v[100:101], v[0:1], 0, v[2:3]
	s_waitcnt vmcnt(1)
	v_fma_f32 v96, v86, v96, v97
	global_load_dword v100, v[100:101], off
	global_store_dword v[82:83], v96, off
	v_or_b32_e32 v96, v107, v91
	v_lshl_add_u64 v[82:83], v[80:81], 0, v[2:3]
	v_lshlrev_b32_e32 v2, 2, v96
	v_lshl_add_u64 v[96:97], v[0:1], 0, v[2:3]
	s_waitcnt vmcnt(1)
	v_fma_f32 v98, v86, v100, v98
	global_load_dword v98, v[96:97], off
	global_store_dword v[82:83], v98, off
	v_or_b32_e32 v96, v104, v92
	v_lshl_add_u64 v[82:83], v[80:81], 0, v[2:3]
	v_lshlrev_b32_e32 v2, 2, v96
	v_lshl_add_u64 v[96:97], v[0:1], 0, v[2:3]
	v_mfma_f32_16x16x32_bf16 v[100:103], v[72:75], v[52:55], 0
	s_waitcnt vmcnt(1)
	v_fmac_f32_e32 v99, v86, v98
	global_load_dword v108, v[96:97], off
	global_store_dword v[82:83], v99, off
	v_mfma_f32_16x16x32_bf16 v[96:99], v[76:79], v[44:47], v[100:103]
	v_lshl_add_u64 v[82:83], v[80:81], 0, v[2:3]
	v_lshlrev_b32_e32 v2, 2, v109
	v_or_b32_e32 v109, v105, v94
	v_lshl_add_u64 v[100:101], v[0:1], 0, v[2:3]
	s_waitcnt vmcnt(1)
	s_nop 2
	v_fma_f32 v96, v86, v108, v96
	global_load_dword v96, v[100:101], off
	global_store_dword v[82:83], v96, off
	v_or_b32_e32 v100, v106, v92
	v_lshl_add_u64 v[82:83], v[80:81], 0, v[2:3]
	v_lshlrev_b32_e32 v2, 2, v100
	v_lshl_add_u64 v[100:101], v[0:1], 0, v[2:3]
	s_waitcnt vmcnt(1)
	v_fma_f32 v96, v86, v96, v97
	global_load_dword v100, v[100:101], off
	global_store_dword v[82:83], v96, off
	v_or_b32_e32 v96, v107, v92
	v_lshl_add_u64 v[82:83], v[80:81], 0, v[2:3]
	v_lshlrev_b32_e32 v2, 2, v96
	v_lshl_add_u64 v[96:97], v[0:1], 0, v[2:3]
	s_waitcnt vmcnt(1)
	v_fma_f32 v98, v86, v100, v98
	global_load_dword v98, v[96:97], off
	global_store_dword v[82:83], v98, off
	v_or_b32_e32 v96, v104, v94
	v_lshl_add_u64 v[82:83], v[80:81], 0, v[2:3]
	v_lshlrev_b32_e32 v2, 2, v96
	v_lshl_add_u64 v[96:97], v[0:1], 0, v[2:3]
	v_mfma_f32_16x16x32_bf16 v[100:103], v[72:75], v[64:67], 0
	s_waitcnt vmcnt(1)
	v_fmac_f32_e32 v99, v86, v98
	global_load_dword v108, v[96:97], off
	global_store_dword v[82:83], v99, off
	v_mfma_f32_16x16x32_bf16 v[96:99], v[76:79], v[60:63], v[100:103]
	v_lshl_add_u64 v[82:83], v[80:81], 0, v[2:3]
	v_lshlrev_b32_e32 v2, 2, v109
	v_or_b32_e32 v109, v105, v93
	v_lshl_add_u64 v[100:101], v[0:1], 0, v[2:3]
	s_waitcnt vmcnt(1)
	s_nop 2
	v_fma_f32 v96, v86, v108, v96
	global_load_dword v96, v[100:101], off
	global_store_dword v[82:83], v96, off
	v_or_b32_e32 v100, v106, v94
	v_lshl_add_u64 v[82:83], v[80:81], 0, v[2:3]
	v_lshlrev_b32_e32 v2, 2, v100
	v_lshl_add_u64 v[100:101], v[0:1], 0, v[2:3]
	s_waitcnt vmcnt(1)
; __device__ __forceinline__ void ssd_states_item(KP P, int l, int seq, int c, int g, char* smem) {
;     ...
;   } else {
;     const int bs = seq - 2;
;     const float* h0 = P->st_ssm + ((long)(l * 8 + bs) * 32 + h) * 8192;
;     float* dst = P->out + O_SSMS + ((long)(l * 8 + bs) * 32 + h) * 8192;
;     const float bd = __expf(tot);
; #pragma unroll
;     for (int mb = 0; mb < 4; ++mb)
; #pragma unroll
;       for (int nb = 0; nb < 8; ++nb)
; #pragma unroll
;         for (int j = 0; j < 4; ++j) {
;           const int o = (mb * 16 + (lane >> 4) * 4 + j) * 128 + nb * 16 + (lane & 15);
;           dst[o] = h0[o] * bd + acc[mb][nb][j];
;         }
	v_fma_f32 v96, v86, v96, v97
	global_load_dword v100, v[100:101], off
	global_store_dword v[82:83], v96, off
	v_or_b32_e32 v96, v107, v94
	v_lshl_add_u64 v[82:83], v[80:81], 0, v[2:3]
	v_lshlrev_b32_e32 v2, 2, v96
	v_lshl_add_u64 v[96:97], v[0:1], 0, v[2:3]
	s_waitcnt vmcnt(1)
	v_fma_f32 v98, v86, v100, v98
	global_load_dword v98, v[96:97], off
	global_store_dword v[82:83], v98, off
	v_or_b32_e32 v96, v104, v93
	v_lshl_add_u64 v[82:83], v[80:81], 0, v[2:3]
	v_lshlrev_b32_e32 v2, 2, v96
	v_lshl_add_u64 v[96:97], v[0:1], 0, v[2:3]
	v_mfma_f32_16x16x32_bf16 v[100:103], v[72:75], v[56:59], 0
	s_waitcnt vmcnt(1)
	v_fmac_f32_e32 v99, v86, v98
	global_load_dword v108, v[96:97], off
	global_store_dword v[82:83], v99, off
	v_mfma_f32_16x16x32_bf16 v[96:99], v[76:79], v[48:51], v[100:103]
	v_lshl_add_u64 v[82:83], v[80:81], 0, v[2:3]
	v_lshlrev_b32_e32 v2, 2, v109
	v_or_b32_e32 v109, v105, v90
	v_lshl_add_u64 v[100:101], v[0:1], 0, v[2:3]
	s_waitcnt vmcnt(1)
	s_nop 2
	v_fma_f32 v96, v86, v108, v96
	global_load_dword v96, v[100:101], off
	global_store_dword v[82:83], v96, off
	v_or_b32_e32 v100, v106, v93
	v_lshl_add_u64 v[82:83], v[80:81], 0, v[2:3]
	v_lshlrev_b32_e32 v2, 2, v100
	v_lshl_add_u64 v[100:101], v[0:1], 0, v[2:3]
	s_waitcnt vmcnt(1)
	v_fma_f32 v96, v86, v96, v97
	global_load_dword v100, v[100:101], off
	global_store_dword v[82:83], v96, off
	v_or_b32_e32 v96, v107, v93
	v_lshl_add_u64 v[82:83], v[80:81], 0, v[2:3]
	v_lshlrev_b32_e32 v2, 2, v96
	v_lshl_add_u64 v[96:97], v[0:1], 0, v[2:3]
	s_waitcnt vmcnt(1)
	v_fma_f32 v98, v86, v100, v98
	global_load_dword v98, v[96:97], off
	global_store_dword v[82:83], v98, off
	v_or_b32_e32 v96, v104, v90
	v_lshl_add_u64 v[82:83], v[80:81], 0, v[2:3]
	v_lshlrev_b32_e32 v2, 2, v96
	v_lshl_add_u64 v[96:97], v[0:1], 0, v[2:3]
	v_mfma_f32_16x16x32_bf16 v[100:103], v[72:75], v[36:39], 0
	s_waitcnt vmcnt(1)
	v_fmac_f32_e32 v99, v86, v98
	global_load_dword v108, v[96:97], off
	global_store_dword v[82:83], v99, off
	v_mfma_f32_16x16x32_bf16 v[96:99], v[76:79], v[28:31], v[100:103]
	v_lshl_add_u64 v[82:83], v[80:81], 0, v[2:3]
	v_lshlrev_b32_e32 v2, 2, v109
	v_or_b32_e32 v109, v105, v89
	v_lshl_add_u64 v[100:101], v[0:1], 0, v[2:3]
	s_waitcnt vmcnt(1)
	s_nop 2
	v_fma_f32 v96, v86, v108, v96
	global_load_dword v96, v[100:101], off
	global_store_dword v[82:83], v96, off
	v_or_b32_e32 v100, v106, v90
	v_lshl_add_u64 v[82:83], v[80:81], 0, v[2:3]
	v_lshlrev_b32_e32 v2, 2, v100
	v_lshl_add_u64 v[100:101], v[0:1], 0, v[2:3]
	s_waitcnt vmcnt(1)
	v_fma_f32 v96, v86, v96, v97
	global_load_dword v100, v[100:101], off
	global_store_dword v[82:83], v96, off
	v_or_b32_e32 v96, v107, v90
	v_lshl_add_u64 v[82:83], v[80:81], 0, v[2:3]
	v_lshlrev_b32_e32 v2, 2, v96
	v_lshl_add_u64 v[96:97], v[0:1], 0, v[2:3]
	s_waitcnt vmcnt(1)
	v_fma_f32 v98, v86, v100, v98
	global_load_dword v98, v[96:97], off
	global_store_dword v[82:83], v98, off
	v_or_b32_e32 v96, v104, v89
	v_lshl_add_u64 v[82:83], v[80:81], 0, v[2:3]
	v_lshlrev_b32_e32 v2, 2, v96
	v_lshl_add_u64 v[96:97], v[0:1], 0, v[2:3]
	v_mfma_f32_16x16x32_bf16 v[100:103], v[72:75], v[24:27], 0
	s_waitcnt vmcnt(1)
	v_fmac_f32_e32 v99, v86, v98
	global_load_dword v108, v[96:97], off
	global_store_dword v[82:83], v99, off
	v_mfma_f32_16x16x32_bf16 v[96:99], v[76:79], v[20:23], v[100:103]
	v_lshl_add_u64 v[82:83], v[80:81], 0, v[2:3]
	v_lshlrev_b32_e32 v2, 2, v109
	v_or_b32_e32 v109, 0x1100, v87
	v_lshl_add_u64 v[100:101], v[0:1], 0, v[2:3]
	v_mfma_f32_16x16x32_bf16 v[72:75], v[72:75], v[16:19], 0
	s_waitcnt vmcnt(1)
	s_nop 1
	v_fma_f32 v96, v86, v108, v96
	global_load_dword v96, v[100:101], off
	global_store_dword v[82:83], v96, off
	v_or_b32_e32 v100, v106, v89
	v_lshl_add_u64 v[82:83], v[80:81], 0, v[2:3]
	v_lshlrev_b32_e32 v2, 2, v100
	v_lshl_add_u64 v[100:101], v[0:1], 0, v[2:3]
	v_mfma_f32_16x16x32_bf16 v[72:75], v[76:79], v[12:15], v[72:75]
	v_or_b32_e32 v108, 0x1080, v87
	s_waitcnt vmcnt(1)
	v_fma_f32 v96, v86, v96, v97
	global_load_dword v100, v[100:101], off
	global_store_dword v[82:83], v96, off
	v_or_b32_e32 v96, v107, v89
	v_lshl_add_u64 v[82:83], v[80:81], 0, v[2:3]
	v_lshlrev_b32_e32 v2, 2, v96
	v_lshl_add_u64 v[96:97], v[0:1], 0, v[2:3]
	s_waitcnt vmcnt(1)
	v_fma_f32 v98, v86, v100, v98
	global_load_dword v98, v[96:97], off
	global_store_dword v[82:83], v98, off
	v_or_b32_e32 v96, v104, v88
	v_lshl_add_u64 v[82:83], v[80:81], 0, v[2:3]
	v_lshlrev_b32_e32 v2, 2, v96
	v_lshl_add_u64 v[96:97], v[0:1], 0, v[2:3]
	v_lshl_add_u64 v[76:77], v[80:81], 0, v[2:3]
	s_waitcnt vmcnt(1)
	v_fmac_f32_e32 v99, v86, v98
	global_store_dword v[82:83], v99, off
	global_load_dword v82, v[96:97], off
	v_or_b32_e32 v83, v105, v88
	v_lshlrev_b32_e32 v2, 2, v83
	v_lshl_add_u64 v[78:79], v[0:1], 0, v[2:3]
	s_waitcnt vmcnt(0)
	v_fma_f32 v72, v86, v82, v72
	global_load_dword v72, v[78:79], off
	global_store_dword v[76:77], v72, off
	v_or_b32_e32 v78, v106, v88
	v_lshl_add_u64 v[76:77], v[80:81], 0, v[2:3]
	v_lshlrev_b32_e32 v2, 2, v78
	v_lshl_add_u64 v[78:79], v[0:1], 0, v[2:3]
	v_or_b32_e32 v82, v108, v85
	s_waitcnt vmcnt(1)
	v_fma_f32 v72, v86, v72, v73
	global_load_dword v78, v[78:79], off
	global_store_dword v[76:77], v72, off
	v_or_b32_e32 v76, v107, v88
	v_lshl_add_u64 v[72:73], v[80:81], 0, v[2:3]
	v_lshlrev_b32_e32 v2, 2, v76
	v_lshl_add_u64 v[76:77], v[0:1], 0, v[2:3]
	s_waitcnt vmcnt(1)
	v_fma_f32 v74, v86, v78, v74
	global_store_dword v[72:73], v74, off
	global_load_dword v73, v[76:77], off
	v_or_b32_e32 v72, 0x1000, v87
	v_or_b32_e32 v74, v72, v85
	v_lshl_add_u64 v[76:77], v[80:81], 0, v[2:3]
	v_lshlrev_b32_e32 v2, 2, v74
	v_lshl_add_u64 v[78:79], v[0:1], 0, v[2:3]
	s_waitcnt vmcnt(0)
; __device__ __forceinline__ void ssd_states_item(KP P, int l, int seq, int c, int g, char* smem) {
;     ...
;   } else {
;     const int bs = seq - 2;
;     const float* h0 = P->st_ssm + ((long)(l * 8 + bs) * 32 + h) * 8192;
;     float* dst = P->out + O_SSMS + ((long)(l * 8 + bs) * 32 + h) * 8192;
;     const float bd = __expf(tot);
; #pragma unroll
;     for (int mb = 0; mb < 4; ++mb)
; #pragma unroll
;       for (int nb = 0; nb < 8; ++nb)
; #pragma unroll
;         for (int j = 0; j < 4; ++j) {
;           const int o = (mb * 16 + (lane >> 4) * 4 + j) * 128 + nb * 16 + (lane & 15);
;           dst[o] = h0[o] * bd + acc[mb][nb][j];
;         }
	v_fmac_f32_e32 v75, v86, v73
	global_load_dword v73, v[78:79], off
	global_store_dword v[76:77], v75, off
	ds_read_b64_tr_b16 v[74:75], v95 offset:17472
	ds_read_b64_tr_b16 v[76:77], v95 offset:18048
	ds_read_b64_tr_b16 v[96:97], v95 offset:22080
	ds_read_b64_tr_b16 v[98:99], v95 offset:22656
	s_waitcnt lgkmcnt(2)
	v_mfma_f32_16x16x32_bf16 v[100:103], v[74:77], v[68:71], 0
	v_lshl_add_u64 v[78:79], v[80:81], 0, v[2:3]
	v_lshlrev_b32_e32 v2, 2, v82
	v_lshl_add_u64 v[82:83], v[0:1], 0, v[2:3]
	s_waitcnt lgkmcnt(0)
	v_mfma_f32_16x16x32_bf16 v[100:103], v[96:99], v[8:11], v[100:103]
	v_mfma_f32_16x16x32_bf16 v[104:107], v[74:77], v[40:43], 0
	s_waitcnt vmcnt(1)
	s_nop 5
	v_fma_f32 v73, v86, v73, v100
	global_load_dword v73, v[82:83], off
	global_store_dword v[78:79], v73, off
	v_or_b32_e32 v82, v109, v85
	v_lshl_add_u64 v[78:79], v[80:81], 0, v[2:3]
	v_lshlrev_b32_e32 v2, 2, v82
	v_lshl_add_u64 v[82:83], v[0:1], 0, v[2:3]
	s_waitcnt vmcnt(1)
	v_fma_f32 v73, v86, v73, v101
	global_load_dword v73, v[82:83], off
	global_store_dword v[78:79], v73, off
	v_or_b32_e32 v82, v110, v85
	v_lshl_add_u64 v[78:79], v[80:81], 0, v[2:3]
	v_lshlrev_b32_e32 v2, 2, v82
	v_lshl_add_u64 v[82:83], v[0:1], 0, v[2:3]
	s_waitcnt vmcnt(1)
	v_fma_f32 v73, v86, v73, v102
	global_load_dword v73, v[82:83], off
	global_store_dword v[78:79], v73, off
	v_or_b32_e32 v82, v72, v91
	v_lshl_add_u64 v[78:79], v[80:81], 0, v[2:3]
	v_lshlrev_b32_e32 v2, 2, v82
	v_lshl_add_u64 v[82:83], v[0:1], 0, v[2:3]
	s_waitcnt vmcnt(1)
	v_fmac_f32_e32 v103, v86, v73
	global_load_dword v73, v[82:83], off
	global_store_dword v[78:79], v103, off
	v_mfma_f32_16x16x32_bf16 v[100:103], v[96:99], v[32:35], v[104:107]
	v_or_b32_e32 v82, v108, v91
	v_lshl_add_u64 v[78:79], v[80:81], 0, v[2:3]
	v_lshlrev_b32_e32 v2, 2, v82
	v_lshl_add_u64 v[82:83], v[0:1], 0, v[2:3]
	v_mfma_f32_16x16x32_bf16 v[104:107], v[74:77], v[52:55], 0
	s_waitcnt vmcnt(1)
	s_nop 1
	v_fma_f32 v73, v86, v73, v100
	global_load_dword v73, v[82:83], off
	global_store_dword v[78:79], v73, off
	v_or_b32_e32 v82, v109, v91
	v_lshl_add_u64 v[78:79], v[80:81], 0, v[2:3]
	v_lshlrev_b32_e32 v2, 2, v82
	v_lshl_add_u64 v[82:83], v[0:1], 0, v[2:3]
	s_waitcnt vmcnt(1)
	v_fma_f32 v73, v86, v73, v101
	global_load_dword v73, v[82:83], off
	global_store_dword v[78:79], v73, off
	v_or_b32_e32 v82, v110, v91
	v_lshl_add_u64 v[78:79], v[80:81], 0, v[2:3]
	v_lshlrev_b32_e32 v2, 2, v82
	v_lshl_add_u64 v[82:83], v[0:1], 0, v[2:3]
	s_waitcnt vmcnt(1)
	v_fma_f32 v73, v86, v73, v102
	global_load_dword v73, v[82:83], off
	global_store_dword v[78:79], v73, off
	v_or_b32_e32 v82, v72, v92
	v_lshl_add_u64 v[78:79], v[80:81], 0, v[2:3]
	v_lshlrev_b32_e32 v2, 2, v82
	v_lshl_add_u64 v[82:83], v[0:1], 0, v[2:3]
	s_waitcnt vmcnt(1)
	v_fmac_f32_e32 v103, v86, v73
	global_load_dword v73, v[82:83], off
	global_store_dword v[78:79], v103, off
	v_mfma_f32_16x16x32_bf16 v[100:103], v[96:99], v[44:47], v[104:107]
	v_or_b32_e32 v82, v108, v92
	v_lshl_add_u64 v[78:79], v[80:81], 0, v[2:3]
	v_lshlrev_b32_e32 v2, 2, v82
	v_lshl_add_u64 v[82:83], v[0:1], 0, v[2:3]
	v_mfma_f32_16x16x32_bf16 v[104:107], v[74:77], v[64:67], 0
	s_waitcnt vmcnt(1)
	s_nop 1
	v_fma_f32 v73, v86, v73, v100
	global_load_dword v73, v[82:83], off
	global_store_dword v[78:79], v73, off
	v_or_b32_e32 v82, v109, v92
	v_lshl_add_u64 v[78:79], v[80:81], 0, v[2:3]
	v_lshlrev_b32_e32 v2, 2, v82
	v_lshl_add_u64 v[82:83], v[0:1], 0, v[2:3]
	s_waitcnt vmcnt(1)
	v_fma_f32 v73, v86, v73, v101
	global_load_dword v73, v[82:83], off
	global_store_dword v[78:79], v73, off
	v_or_b32_e32 v82, v110, v92
	v_lshl_add_u64 v[78:79], v[80:81], 0, v[2:3]
	v_lshlrev_b32_e32 v2, 2, v82
	v_lshl_add_u64 v[82:83], v[0:1], 0, v[2:3]
	s_waitcnt vmcnt(1)
	v_fma_f32 v73, v86, v73, v102
	global_load_dword v73, v[82:83], off
	global_store_dword v[78:79], v73, off
	v_or_b32_e32 v82, v72, v94
	v_lshl_add_u64 v[78:79], v[80:81], 0, v[2:3]
	v_lshlrev_b32_e32 v2, 2, v82
	v_lshl_add_u64 v[82:83], v[0:1], 0, v[2:3]
	s_waitcnt vmcnt(1)
	v_fmac_f32_e32 v103, v86, v73
	global_load_dword v73, v[82:83], off
	global_store_dword v[78:79], v103, off
	v_mfma_f32_16x16x32_bf16 v[100:103], v[96:99], v[60:63], v[104:107]
	v_or_b32_e32 v82, v108, v94
	v_lshl_add_u64 v[78:79], v[80:81], 0, v[2:3]
	v_lshlrev_b32_e32 v2, 2, v82
	v_lshl_add_u64 v[82:83], v[0:1], 0, v[2:3]
	v_mfma_f32_16x16x32_bf16 v[104:107], v[74:77], v[56:59], 0
	s_waitcnt vmcnt(1)
	s_nop 1
	v_fma_f32 v73, v86, v73, v100
	global_load_dword v73, v[82:83], off
	global_store_dword v[78:79], v73, off
	v_or_b32_e32 v82, v109, v94
	v_lshl_add_u64 v[78:79], v[80:81], 0, v[2:3]
	v_lshlrev_b32_e32 v2, 2, v82
	v_lshl_add_u64 v[82:83], v[0:1], 0, v[2:3]
	s_waitcnt vmcnt(1)
	v_fma_f32 v73, v86, v73, v101
	global_load_dword v73, v[82:83], off
	global_store_dword v[78:79], v73, off
	v_or_b32_e32 v82, v110, v94
	v_lshl_add_u64 v[78:79], v[80:81], 0, v[2:3]
	v_lshlrev_b32_e32 v2, 2, v82
	v_lshl_add_u64 v[82:83], v[0:1], 0, v[2:3]
	s_waitcnt vmcnt(1)
	v_fma_f32 v73, v86, v73, v102
	global_load_dword v73, v[82:83], off
	global_store_dword v[78:79], v73, off
	v_or_b32_e32 v82, v72, v93
	v_lshl_add_u64 v[78:79], v[80:81], 0, v[2:3]
	v_lshlrev_b32_e32 v2, 2, v82
	v_lshl_add_u64 v[82:83], v[0:1], 0, v[2:3]
	s_waitcnt vmcnt(1)
	v_fmac_f32_e32 v103, v86, v73
	global_load_dword v73, v[82:83], off
	global_store_dword v[78:79], v103, off
	v_mfma_f32_16x16x32_bf16 v[100:103], v[96:99], v[48:51], v[104:107]
	v_or_b32_e32 v82, v108, v93
	v_lshl_add_u64 v[78:79], v[80:81], 0, v[2:3]
	v_lshlrev_b32_e32 v2, 2, v82
	v_lshl_add_u64 v[82:83], v[0:1], 0, v[2:3]
	v_mfma_f32_16x16x32_bf16 v[104:107], v[74:77], v[36:39], 0
	s_waitcnt vmcnt(1)
; __device__ __forceinline__ void ssd_states_item(KP P, int l, int seq, int c, int g, char* smem) {
;     ...
;   } else {
;     const int bs = seq - 2;
;     const float* h0 = P->st_ssm + ((long)(l * 8 + bs) * 32 + h) * 8192;
;     float* dst = P->out + O_SSMS + ((long)(l * 8 + bs) * 32 + h) * 8192;
;     const float bd = __expf(tot);
; #pragma unroll
;     for (int mb = 0; mb < 4; ++mb)
; #pragma unroll
;       for (int nb = 0; nb < 8; ++nb)
; #pragma unroll
;         for (int j = 0; j < 4; ++j) {
;           const int o = (mb * 16 + (lane >> 4) * 4 + j) * 128 + nb * 16 + (lane & 15);
;           dst[o] = h0[o] * bd + acc[mb][nb][j];
;         }
	s_nop 1
	v_fma_f32 v73, v86, v73, v100
	global_load_dword v73, v[82:83], off
	global_store_dword v[78:79], v73, off
	v_or_b32_e32 v82, v109, v93
	v_lshl_add_u64 v[78:79], v[80:81], 0, v[2:3]
	v_lshlrev_b32_e32 v2, 2, v82
	v_lshl_add_u64 v[82:83], v[0:1], 0, v[2:3]
	s_waitcnt vmcnt(1)
	v_fma_f32 v73, v86, v73, v101
	global_load_dword v73, v[82:83], off
	global_store_dword v[78:79], v73, off
	v_or_b32_e32 v82, v110, v93
	v_lshl_add_u64 v[78:79], v[80:81], 0, v[2:3]
	v_lshlrev_b32_e32 v2, 2, v82
	v_lshl_add_u64 v[82:83], v[0:1], 0, v[2:3]
	s_waitcnt vmcnt(1)
	v_fma_f32 v73, v86, v73, v102
	global_load_dword v73, v[82:83], off
	global_store_dword v[78:79], v73, off
	v_or_b32_e32 v82, v72, v90
	v_lshl_add_u64 v[78:79], v[80:81], 0, v[2:3]
	v_lshlrev_b32_e32 v2, 2, v82
	v_lshl_add_u64 v[82:83], v[0:1], 0, v[2:3]
	s_waitcnt vmcnt(1)
	v_fmac_f32_e32 v103, v86, v73
	global_load_dword v73, v[82:83], off
	global_store_dword v[78:79], v103, off
	v_mfma_f32_16x16x32_bf16 v[100:103], v[96:99], v[28:31], v[104:107]
	v_or_b32_e32 v82, v108, v90
	v_lshl_add_u64 v[78:79], v[80:81], 0, v[2:3]
	v_lshlrev_b32_e32 v2, 2, v82
	v_lshl_add_u64 v[82:83], v[0:1], 0, v[2:3]
	v_mfma_f32_16x16x32_bf16 v[104:107], v[74:77], v[24:27], 0
	s_waitcnt vmcnt(1)
	s_nop 1
	v_fma_f32 v73, v86, v73, v100
	global_load_dword v73, v[82:83], off
	global_store_dword v[78:79], v73, off
	v_or_b32_e32 v82, v109, v90
	v_lshl_add_u64 v[78:79], v[80:81], 0, v[2:3]
	v_lshlrev_b32_e32 v2, 2, v82
	v_lshl_add_u64 v[82:83], v[0:1], 0, v[2:3]
	s_waitcnt vmcnt(1)
	v_fma_f32 v73, v86, v73, v101
	global_load_dword v73, v[82:83], off
	global_store_dword v[78:79], v73, off
	v_or_b32_e32 v82, v110, v90
	v_lshl_add_u64 v[78:79], v[80:81], 0, v[2:3]
	v_lshlrev_b32_e32 v2, 2, v82
	v_lshl_add_u64 v[82:83], v[0:1], 0, v[2:3]
	s_waitcnt vmcnt(1)
	v_fma_f32 v73, v86, v73, v102
	global_load_dword v73, v[82:83], off
	global_store_dword v[78:79], v73, off
	v_or_b32_e32 v82, v72, v89
	v_lshl_add_u64 v[78:79], v[80:81], 0, v[2:3]
	v_lshlrev_b32_e32 v2, 2, v82
	v_lshl_add_u64 v[82:83], v[0:1], 0, v[2:3]
	s_waitcnt vmcnt(1)
	v_fmac_f32_e32 v103, v86, v73
	global_load_dword v73, v[82:83], off
	global_store_dword v[78:79], v103, off
	v_mfma_f32_16x16x32_bf16 v[100:103], v[96:99], v[20:23], v[104:107]
	v_or_b32_e32 v82, v108, v89
	v_lshl_add_u64 v[78:79], v[80:81], 0, v[2:3]
	v_lshlrev_b32_e32 v2, 2, v82
	v_lshl_add_u64 v[82:83], v[0:1], 0, v[2:3]
	s_waitcnt vmcnt(1)
	s_nop 2
	v_fma_f32 v73, v86, v73, v100
	global_load_dword v73, v[82:83], off
	global_store_dword v[78:79], v73, off
	v_or_b32_e32 v82, v109, v89
	v_lshl_add_u64 v[78:79], v[80:81], 0, v[2:3]
	v_lshlrev_b32_e32 v2, 2, v82
	v_lshl_add_u64 v[82:83], v[0:1], 0, v[2:3]
	s_waitcnt vmcnt(1)
	v_fma_f32 v73, v86, v73, v101
	global_load_dword v73, v[82:83], off
	global_store_dword v[78:79], v73, off
	v_or_b32_e32 v82, v110, v89
	v_lshl_add_u64 v[78:79], v[80:81], 0, v[2:3]
	v_lshlrev_b32_e32 v2, 2, v82
	v_lshl_add_u64 v[82:83], v[0:1], 0, v[2:3]
	s_waitcnt vmcnt(1)
	v_fma_f32 v73, v86, v73, v102
	global_load_dword v82, v[82:83], off
	global_store_dword v[78:79], v73, off
	v_or_b32_e32 v78, v72, v88
	v_mfma_f32_16x16x32_bf16 v[72:75], v[74:77], v[16:19], 0
	v_lshl_add_u64 v[76:77], v[80:81], 0, v[2:3]
	v_lshlrev_b32_e32 v2, 2, v78
	v_lshl_add_u64 v[78:79], v[0:1], 0, v[2:3]
	v_mfma_f32_16x16x32_bf16 v[72:75], v[96:99], v[12:15], v[72:75]
	s_waitcnt vmcnt(1)
	v_fmac_f32_e32 v103, v86, v82
	global_load_dword v82, v[78:79], off
	global_store_dword v[76:77], v103, off
	v_or_b32_e32 v78, v108, v88
	v_lshl_add_u64 v[76:77], v[80:81], 0, v[2:3]
	v_lshlrev_b32_e32 v2, 2, v78
	v_lshl_add_u64 v[78:79], v[0:1], 0, v[2:3]
	s_waitcnt vmcnt(1)
	v_fma_f32 v72, v86, v82, v72
	global_load_dword v72, v[78:79], off
	global_store_dword v[76:77], v72, off
	v_or_b32_e32 v78, v109, v88
	v_lshl_add_u64 v[76:77], v[80:81], 0, v[2:3]
	v_lshlrev_b32_e32 v2, 2, v78
	v_lshl_add_u64 v[78:79], v[0:1], 0, v[2:3]
	v_or_b32_e32 v82, 0x1800, v87
	s_waitcnt vmcnt(1)
	v_fma_f32 v72, v86, v72, v73
	global_load_dword v78, v[78:79], off
	global_store_dword v[76:77], v72, off
	v_or_b32_e32 v76, v110, v88
	v_lshl_add_u64 v[72:73], v[80:81], 0, v[2:3]
	v_lshlrev_b32_e32 v2, 2, v76
	v_lshl_add_u64 v[76:77], v[0:1], 0, v[2:3]
	s_waitcnt vmcnt(1)
	v_fma_f32 v74, v86, v78, v74
	global_load_dword v74, v[76:77], off
	global_store_dword v[72:73], v74, off
	v_or_b32_e32 v76, v82, v85
	v_lshl_add_u64 v[72:73], v[80:81], 0, v[2:3]
	v_lshlrev_b32_e32 v2, 2, v76
	v_lshl_add_u64 v[76:77], v[0:1], 0, v[2:3]
	s_waitcnt vmcnt(1)
	v_fmac_f32_e32 v75, v86, v74
	global_load_dword v83, v[76:77], off
	global_store_dword v[72:73], v75, off
	ds_read_b64_tr_b16 v[72:73], v95 offset:17504
	ds_read_b64_tr_b16 v[74:75], v95 offset:18080
	ds_read_b64_tr_b16 v[76:77], v95 offset:22112
	ds_read_b64_tr_b16 v[78:79], v95 offset:22688
	s_waitcnt lgkmcnt(2)
	v_mfma_f32_16x16x32_bf16 v[68:71], v[72:75], v[68:71], 0
	v_or_b32_e32 v95, 0x1880, v87
	v_or_b32_e32 v96, v95, v85
	s_waitcnt lgkmcnt(0)
	v_mfma_f32_16x16x32_bf16 v[8:11], v[76:79], v[8:11], v[68:71]
	s_nop 3
	v_lshl_add_u64 v[68:69], v[80:81], 0, v[2:3]
	v_lshlrev_b32_e32 v2, 2, v96
	v_lshl_add_u64 v[70:71], v[0:1], 0, v[2:3]
	v_mfma_f32_16x16x32_bf16 v[40:43], v[72:75], v[40:43], 0
	s_waitcnt vmcnt(1)
	v_fma_f32 v8, v86, v83, v8
	global_load_dword v8, v[70:71], off
	global_store_dword v[68:69], v8, off
	v_or_b32_e32 v83, 0x1900, v87
	v_or_b32_e32 v70, v83, v85
	v_lshl_add_u64 v[68:69], v[80:81], 0, v[2:3]
	v_lshlrev_b32_e32 v2, 2, v70
	v_lshl_add_u64 v[70:71], v[0:1], 0, v[2:3]
	v_mfma_f32_16x16x32_bf16 v[24:27], v[72:75], v[24:27], 0
	s_waitcnt vmcnt(1)
; __device__ __forceinline__ void ssd_states_item(KP P, int l, int seq, int c, int g, char* smem) {
;     ...
;   } else {
;     const int bs = seq - 2;
;     const float* h0 = P->st_ssm + ((long)(l * 8 + bs) * 32 + h) * 8192;
;     float* dst = P->out + O_SSMS + ((long)(l * 8 + bs) * 32 + h) * 8192;
;     const float bd = __expf(tot);
; #pragma unroll
;     for (int mb = 0; mb < 4; ++mb)
; #pragma unroll
;       for (int nb = 0; nb < 8; ++nb)
; #pragma unroll
;         for (int j = 0; j < 4; ++j) {
;           const int o = (mb * 16 + (lane >> 4) * 4 + j) * 128 + nb * 16 + (lane & 15);
;           dst[o] = h0[o] * bd + acc[mb][nb][j];
;         }
	v_fma_f32 v8, v86, v8, v9
	global_load_dword v70, v[70:71], off
	global_store_dword v[68:69], v8, off
	v_or_b32_e32 v71, 0x1980, v87
	v_or_b32_e32 v68, v71, v85
	v_lshl_add_u64 v[8:9], v[80:81], 0, v[2:3]
	v_lshlrev_b32_e32 v2, 2, v68
	v_lshl_add_u64 v[68:69], v[0:1], 0, v[2:3]
	v_mfma_f32_16x16x32_bf16 v[16:19], v[72:75], v[16:19], 0
	s_waitcnt vmcnt(1)
	v_fma_f32 v10, v86, v70, v10
	global_load_dword v10, v[68:69], off
	global_store_dword v[8:9], v10, off
	v_or_b32_e32 v68, v82, v91
	v_lshl_add_u64 v[8:9], v[80:81], 0, v[2:3]
	v_lshlrev_b32_e32 v2, 2, v68
	v_lshl_add_u64 v[68:69], v[0:1], 0, v[2:3]
	s_waitcnt vmcnt(1)
	v_fmac_f32_e32 v11, v86, v10
	global_load_dword v68, v[68:69], off
	global_store_dword v[8:9], v11, off
	v_mfma_f32_16x16x32_bf16 v[8:11], v[76:79], v[32:35], v[40:43]
	v_or_b32_e32 v69, v95, v91
	v_lshl_add_u64 v[32:33], v[80:81], 0, v[2:3]
	v_lshlrev_b32_e32 v2, 2, v69
	v_lshl_add_u64 v[34:35], v[0:1], 0, v[2:3]
	v_or_b32_e32 v40, v82, v92
	s_waitcnt vmcnt(1)
	s_nop 1
	v_fma_f32 v8, v86, v68, v8
	global_load_dword v8, v[34:35], off
	global_store_dword v[32:33], v8, off
	v_or_b32_e32 v34, v83, v91
	v_lshl_add_u64 v[32:33], v[80:81], 0, v[2:3]
	v_lshlrev_b32_e32 v2, 2, v34
	v_lshl_add_u64 v[34:35], v[0:1], 0, v[2:3]
	s_waitcnt vmcnt(1)
	v_fma_f32 v8, v86, v8, v9
	global_load_dword v34, v[34:35], off
	global_store_dword v[32:33], v8, off
	v_or_b32_e32 v32, v71, v91
	v_lshl_add_u64 v[8:9], v[80:81], 0, v[2:3]
	v_lshlrev_b32_e32 v2, 2, v32
	v_lshl_add_u64 v[32:33], v[0:1], 0, v[2:3]
	s_waitcnt vmcnt(1)
	v_fma_f32 v10, v86, v34, v10
	global_load_dword v10, v[32:33], off
	global_store_dword v[8:9], v10, off
	v_lshl_add_u64 v[8:9], v[80:81], 0, v[2:3]
	v_lshlrev_b32_e32 v2, 2, v40
	v_lshl_add_u64 v[40:41], v[0:1], 0, v[2:3]
	v_mfma_f32_16x16x32_bf16 v[32:35], v[72:75], v[52:55], 0
	v_mov_b32_e32 v52, 0
	s_waitcnt vmcnt(1)
	v_fmac_f32_e32 v11, v86, v10
	global_load_dword v40, v[40:41], off
	global_store_dword v[8:9], v11, off
	v_mfma_f32_16x16x32_bf16 v[8:11], v[76:79], v[44:47], v[32:35]
	v_or_b32_e32 v41, v95, v92
	s_nop 1
	v_lshl_add_u64 v[32:33], v[80:81], 0, v[2:3]
	v_lshlrev_b32_e32 v2, 2, v41
	v_lshl_add_u64 v[34:35], v[0:1], 0, v[2:3]
	s_waitcnt vmcnt(1)
	s_nop 0
	v_fma_f32 v8, v86, v40, v8
	global_load_dword v8, v[34:35], off
	global_store_dword v[32:33], v8, off
	v_or_b32_e32 v34, v83, v92
	v_lshl_add_u64 v[32:33], v[80:81], 0, v[2:3]
	v_lshlrev_b32_e32 v2, 2, v34
	v_lshl_add_u64 v[34:35], v[0:1], 0, v[2:3]
	v_or_b32_e32 v40, v82, v94
	s_waitcnt vmcnt(1)
	v_fma_f32 v8, v86, v8, v9
	global_load_dword v34, v[34:35], off
	global_store_dword v[32:33], v8, off
	v_or_b32_e32 v32, v71, v92
	v_lshl_add_u64 v[8:9], v[80:81], 0, v[2:3]
	v_lshlrev_b32_e32 v2, 2, v32
	v_lshl_add_u64 v[32:33], v[0:1], 0, v[2:3]
	s_waitcnt vmcnt(1)
	v_fma_f32 v10, v86, v34, v10
	global_load_dword v10, v[32:33], off
	global_store_dword v[8:9], v10, off
	v_lshl_add_u64 v[8:9], v[80:81], 0, v[2:3]
	v_lshlrev_b32_e32 v2, 2, v40
	v_lshl_add_u64 v[40:41], v[0:1], 0, v[2:3]
	v_mfma_f32_16x16x32_bf16 v[32:35], v[72:75], v[64:67], 0
	s_waitcnt vmcnt(1)
	v_fmac_f32_e32 v11, v86, v10
	global_load_dword v40, v[40:41], off
	global_store_dword v[8:9], v11, off
	v_mfma_f32_16x16x32_bf16 v[8:11], v[76:79], v[60:63], v[32:35]
	v_or_b32_e32 v41, v95, v94
	s_nop 1
	v_lshl_add_u64 v[32:33], v[80:81], 0, v[2:3]
	v_lshlrev_b32_e32 v2, 2, v41
	v_lshl_add_u64 v[34:35], v[0:1], 0, v[2:3]
	s_waitcnt vmcnt(1)
	s_nop 0
	v_fma_f32 v8, v86, v40, v8
	global_load_dword v8, v[34:35], off
	global_store_dword v[32:33], v8, off
	v_or_b32_e32 v34, v83, v94
	v_lshl_add_u64 v[32:33], v[80:81], 0, v[2:3]
	v_lshlrev_b32_e32 v2, 2, v34
	v_lshl_add_u64 v[34:35], v[0:1], 0, v[2:3]
	v_or_b32_e32 v40, v82, v93
	s_waitcnt vmcnt(1)
	v_fma_f32 v8, v86, v8, v9
	global_load_dword v34, v[34:35], off
	global_store_dword v[32:33], v8, off
	v_or_b32_e32 v32, v71, v94
	v_lshl_add_u64 v[8:9], v[80:81], 0, v[2:3]
	v_lshlrev_b32_e32 v2, 2, v32
	v_lshl_add_u64 v[32:33], v[0:1], 0, v[2:3]
	s_waitcnt vmcnt(1)
	v_fma_f32 v10, v86, v34, v10
	global_load_dword v10, v[32:33], off
	global_store_dword v[8:9], v10, off
	v_lshl_add_u64 v[8:9], v[80:81], 0, v[2:3]
	v_lshlrev_b32_e32 v2, 2, v40
	v_lshl_add_u64 v[40:41], v[0:1], 0, v[2:3]
	v_mfma_f32_16x16x32_bf16 v[32:35], v[72:75], v[56:59], 0
	s_waitcnt vmcnt(1)
	v_fmac_f32_e32 v11, v86, v10
	global_load_dword v40, v[40:41], off
	global_store_dword v[8:9], v11, off
	v_mfma_f32_16x16x32_bf16 v[8:11], v[76:79], v[48:51], v[32:35]
	v_or_b32_e32 v41, v95, v93
	s_nop 1
	v_lshl_add_u64 v[32:33], v[80:81], 0, v[2:3]
	v_lshlrev_b32_e32 v2, 2, v41
	v_lshl_add_u64 v[34:35], v[0:1], 0, v[2:3]
	s_waitcnt vmcnt(1)
	s_nop 0
	v_fma_f32 v8, v86, v40, v8
	global_load_dword v8, v[34:35], off
	global_store_dword v[32:33], v8, off
	v_or_b32_e32 v34, v83, v93
	v_lshl_add_u64 v[32:33], v[80:81], 0, v[2:3]
	v_lshlrev_b32_e32 v2, 2, v34
	v_lshl_add_u64 v[34:35], v[0:1], 0, v[2:3]
	v_or_b32_e32 v40, v82, v90
	s_waitcnt vmcnt(1)
; __device__ __forceinline__ void ssd_states_item(KP P, int l, int seq, int c, int g, char* smem) {
;     ...
;   } else {
;     const int bs = seq - 2;
;     const float* h0 = P->st_ssm + ((long)(l * 8 + bs) * 32 + h) * 8192;
;     float* dst = P->out + O_SSMS + ((long)(l * 8 + bs) * 32 + h) * 8192;
;     const float bd = __expf(tot);
; #pragma unroll
;     for (int mb = 0; mb < 4; ++mb)
; #pragma unroll
;       for (int nb = 0; nb < 8; ++nb)
; #pragma unroll
;         for (int j = 0; j < 4; ++j) {
;           const int o = (mb * 16 + (lane >> 4) * 4 + j) * 128 + nb * 16 + (lane & 15);
;           dst[o] = h0[o] * bd + acc[mb][nb][j];
;         }
;   }
;   __syncthreads();
; __device__ __forceinline__ void ssd_out_item(KP P, int l, int seq, int c, int g, char* smem) {
;     ...
;   const float a = -__expf(P->a_log[l * 32 + h]);
;   float dt, acum;
;   ssd_dt_acum(DT, rb, L, h, a, lane, dt, acum);
	v_fma_f32 v8, v86, v8, v9
	global_load_dword v34, v[34:35], off
	global_store_dword v[32:33], v8, off
	v_or_b32_e32 v32, v71, v93
	v_lshl_add_u64 v[8:9], v[80:81], 0, v[2:3]
	v_lshlrev_b32_e32 v2, 2, v32
	v_lshl_add_u64 v[32:33], v[0:1], 0, v[2:3]
	s_waitcnt vmcnt(1)
	v_fma_f32 v10, v86, v34, v10
	global_load_dword v10, v[32:33], off
	global_store_dword v[8:9], v10, off
	v_lshl_add_u64 v[8:9], v[80:81], 0, v[2:3]
	v_lshlrev_b32_e32 v2, 2, v40
	v_mfma_f32_16x16x32_bf16 v[32:35], v[72:75], v[36:39], 0
	v_lshl_add_u64 v[36:37], v[0:1], 0, v[2:3]
	s_waitcnt vmcnt(1)
	v_fmac_f32_e32 v11, v86, v10
	global_load_dword v36, v[36:37], off
	global_store_dword v[8:9], v11, off
	v_mfma_f32_16x16x32_bf16 v[8:11], v[76:79], v[28:31], v[32:35]
	v_or_b32_e32 v37, v95, v90
	v_lshl_add_u64 v[28:29], v[80:81], 0, v[2:3]
	v_lshlrev_b32_e32 v2, 2, v37
	v_lshl_add_u64 v[30:31], v[0:1], 0, v[2:3]
	s_waitcnt vmcnt(1)
	s_nop 2
	v_fma_f32 v8, v86, v36, v8
	global_load_dword v8, v[30:31], off
	global_store_dword v[28:29], v8, off
	v_or_b32_e32 v30, v83, v90
	v_lshl_add_u64 v[28:29], v[80:81], 0, v[2:3]
	v_lshlrev_b32_e32 v2, 2, v30
	v_lshl_add_u64 v[30:31], v[0:1], 0, v[2:3]
	s_waitcnt vmcnt(1)
	v_fma_f32 v8, v86, v8, v9
	global_load_dword v30, v[30:31], off
	global_store_dword v[28:29], v8, off
	v_or_b32_e32 v28, v71, v90
	v_lshl_add_u64 v[8:9], v[80:81], 0, v[2:3]
	v_lshlrev_b32_e32 v2, 2, v28
	v_lshl_add_u64 v[28:29], v[0:1], 0, v[2:3]
	s_waitcnt vmcnt(1)
	v_fma_f32 v10, v86, v30, v10
	global_load_dword v10, v[28:29], off
	global_store_dword v[8:9], v10, off
	v_or_b32_e32 v28, v82, v89
	v_lshl_add_u64 v[8:9], v[80:81], 0, v[2:3]
	v_lshlrev_b32_e32 v2, 2, v28
	v_lshl_add_u64 v[28:29], v[0:1], 0, v[2:3]
	s_waitcnt vmcnt(1)
	v_fmac_f32_e32 v11, v86, v10
	global_load_dword v28, v[28:29], off
	global_store_dword v[8:9], v11, off
	v_mfma_f32_16x16x32_bf16 v[8:11], v[76:79], v[20:23], v[24:27]
	v_or_b32_e32 v29, v95, v89
	v_lshl_add_u64 v[20:21], v[80:81], 0, v[2:3]
	v_lshlrev_b32_e32 v2, 2, v29
	v_lshl_add_u64 v[22:23], v[0:1], 0, v[2:3]
	s_waitcnt vmcnt(1)
	s_nop 2
	v_fma_f32 v8, v86, v28, v8
	global_load_dword v8, v[22:23], off
	global_store_dword v[20:21], v8, off
	v_or_b32_e32 v22, v83, v89
	v_lshl_add_u64 v[20:21], v[80:81], 0, v[2:3]
	v_lshlrev_b32_e32 v2, 2, v22
	v_lshl_add_u64 v[22:23], v[0:1], 0, v[2:3]
	s_waitcnt vmcnt(1)
	v_fma_f32 v8, v86, v8, v9
	global_load_dword v22, v[22:23], off
	global_store_dword v[20:21], v8, off
	v_or_b32_e32 v20, v71, v89
	v_lshl_add_u64 v[8:9], v[80:81], 0, v[2:3]
	v_lshlrev_b32_e32 v2, 2, v20
	v_lshl_add_u64 v[20:21], v[0:1], 0, v[2:3]
	s_waitcnt vmcnt(1)
	v_fma_f32 v10, v86, v22, v10
	global_load_dword v10, v[20:21], off
	global_store_dword v[8:9], v10, off
	v_or_b32_e32 v20, v82, v88
	v_lshl_add_u64 v[8:9], v[80:81], 0, v[2:3]
	v_lshlrev_b32_e32 v2, 2, v20
	v_lshl_add_u64 v[20:21], v[0:1], 0, v[2:3]
	v_mov_b32_e32 v22, v188
	s_waitcnt vmcnt(1)
	v_fmac_f32_e32 v11, v86, v10
	global_load_dword v20, v[20:21], off
	global_store_dword v[8:9], v11, off
	v_mfma_f32_16x16x32_bf16 v[8:11], v[76:79], v[12:15], v[16:19]
	v_or_b32_e32 v21, v95, v88
	v_lshl_add_u64 v[12:13], v[80:81], 0, v[2:3]
	v_lshlrev_b32_e32 v2, 2, v21
	v_lshl_add_u64 v[14:15], v[0:1], 0, v[2:3]
	s_waitcnt vmcnt(1)
	s_nop 2
	v_fma_f32 v8, v86, v20, v8
	global_load_dword v8, v[14:15], off
	global_store_dword v[12:13], v8, off
	v_or_b32_e32 v14, v83, v88
	v_lshl_add_u64 v[12:13], v[80:81], 0, v[2:3]
	v_lshlrev_b32_e32 v2, 2, v14
	v_lshl_add_u64 v[14:15], v[0:1], 0, v[2:3]
	s_waitcnt vmcnt(1)
	v_fma_f32 v8, v86, v8, v9
	global_store_dword v[12:13], v8, off
	global_load_dword v12, v[14:15], off
	v_or_b32_e32 v13, v71, v88
	v_lshl_add_u64 v[8:9], v[80:81], 0, v[2:3]
	v_lshlrev_b32_e32 v2, 2, v13
	v_lshl_add_u64 v[0:1], v[0:1], 0, v[2:3]
	s_waitcnt vmcnt(0)
	v_fma_f32 v10, v86, v12, v10
	global_store_dword v[8:9], v10, off
	global_load_dword v8, v[0:1], off
	v_lshl_add_u64 v[0:1], v[80:81], 0, v[2:3]
	s_waitcnt vmcnt(0)
	v_fmac_f32_e32 v11, v86, v8
	global_store_dword v[0:1], v11, off
	s_barrier
	s_load_dwordx2 s[4:5], s[6:7], 0xd8
	s_load_dwordx2 s[8:9], s[6:7], 0x60
	v_ashrrev_i32_e32 v24, 6, v22
	v_add_u32_e32 v100, s13, v24
	v_add_u32_e32 v104, s44, v100
	v_ashrrev_i32_e32 v105, 31, v104
	s_waitcnt lgkmcnt(0)
	v_lshl_add_u64 v[0:1], v[104:105], 2, s[8:9]
	global_load_dword v0, v[0:1], off
	s_add_u32 s8, s4, s0
	v_and_b32_e32 v23, 63, v22
	s_addc_u32 s9, s5, s1
	v_cmp_gt_u32_e64 s[4:5], 16, v23
	v_ashrrev_i32_e32 v101, 31, v100
	s_and_saveexec_b64 s[0:1], s[4:5]
	s_cbranch_execz .LBB0_566
	v_or_b32_e32 v2, s15, v23
	v_lshlrev_b64 v[8:9], 7, v[2:3]
	v_lshl_add_u64 v[8:9], s[8:9], 0, v[8:9]
	v_lshl_add_u64 v[8:9], v[100:101], 2, v[8:9]
	v_add_co_u32_e32 v8, vcc, 0x34b60000, v8
	s_nop 1
	v_addc_co_u32_e32 v9, vcc, 0, v9, vcc
	global_load_dword v84, v[8:9], off
